# attention: static s_setprio 1 for workgroups blockIdx>=256 (the second resident workgroup of each CU)
# baseline (speedup 1.0000x reference)
.LBB0_1471:
	s_cmpk_gt_i32 s74, 0x5ff
	s_cbranch_scc1 .LBB0_1485
	s_cmpk_lt_u32 s74, 0x100
	s_cbranch_scc1 .Lprio13
	s_setprio 1

.LBB0_1485:
	s_setprio 0
	s_cmp_lt_i32 s76, 15
	s_cselect_b64 s[2:3], -1, 0
	s_cmp_gt_i32 s77, 14
	s_cselect_b64 s[4:5], -1, 0
	s_and_b64 s[4:5], s[2:3], s[4:5]
	s_andn2_b64 vcc, exec, s[4:5]
	s_cbranch_vccnz .LBB0_1552
	s_andn2_b64 vcc, exec, s[0:1]
	s_cbranch_vccnz .LBB0_1540
	s_waitcnt vmcnt(0)
	s_waitcnt lgkmcnt(0)
	s_barrier
	s_mov_b64 s[0:1], exec
	v_readlane_b32 s4, v252, 0
	v_readlane_b32 s5, v252, 1
	s_and_b64 s[4:5], s[0:1], s[4:5]
	s_mov_b64 exec, s[4:5]
	s_cbranch_execz .LBB0_1539
	s_add_i32 s4, 0, 0x137f0
	v_mov_b32_e32 v0, s4
	s_waitcnt vmcnt(0) expcnt(0) lgkmcnt(0)
	ds_read_b32 v2, v0
	s_add_i32 s4, 0, 0x137f4
	v_mov_b32_e32 v0, s4
	ds_read_b32 v0, v0
	s_waitcnt lgkmcnt(1)
	v_cmp_ne_u32_e32 vcc, 0, v2
	s_cbranch_vccnz .LBB0_1503
	s_load_dwordx2 s[8:9], s[78:79], 0xc8
	s_load_dword s7, s[78:79], 0xd0
	s_add_u32 s4, s94, 0x28200
	s_addc_u32 s5, s95, 0
	s_add_u32 s6, s94, 0x28400
	s_waitcnt lgkmcnt(0)
	s_mul_i32 s33, s9, s8
	s_mul_i32 s33, s33, s7
	s_addc_u32 s7, s95, 0
	s_add_u32 s8, s94, 0x28500
	s_addc_u32 s9, s95, 0
	s_add_u32 s10, s94, 0x28600
	s_addc_u32 s11, s95, 0
	s_add_u32 s12, s94, 0x28700
	s_addc_u32 s13, s95, 0
	s_add_u32 s14, s94, 0x28800
	s_addc_u32 s15, s95, 0
	s_add_u32 s16, s94, 0x28900
	s_addc_u32 s17, s95, 0
	s_add_u32 s18, s94, 0x28a00
	s_addc_u32 s19, s95, 0
	s_add_u32 s20, s94, 0x28b00
	s_addc_u32 s21, s95, 0
	s_add_u32 s22, s94, 0x28c00
	s_addc_u32 s23, s95, 0
	s_add_u32 s24, s94, 0x28d00
	s_addc_u32 s25, s95, 0
	s_add_u32 s26, s94, 0x28e00
	s_addc_u32 s27, s95, 0
	s_add_u32 s28, s94, 0x28f00
	s_addc_u32 s29, s95, 0
	s_add_u32 s30, s94, 0x29000
	s_addc_u32 s31, s95, 0
	s_add_u32 s34, s94, 0x29100
	s_addc_u32 s35, s95, 0
	s_add_u32 s36, s94, 0x29200
	s_addc_u32 s37, s95, 0
	s_add_u32 s38, s94, 0x29300
	s_addc_u32 s39, s95, 0
	s_mov_b32 s46, 1
	v_mov_b32_e32 v16, 0
	s_branch .LBB0_1491
